# conversion phase: the four 32-tile NSA w1 strip jobs swapped with four down-strip jobs so no CU gets a long job as its second job
# speedup vs baseline: 1.0099x; 1.0099x over previous
; DI void convert_phase(int wv, const P& p_, int L, LAS unsigned char* lds) {
;     ...
;   for (int j = blockIdx.x; j < njobs; j += gridDim.x) {
;     if (j < 272) {
;       const int f = j / 136, jj = j % 136;
.LBB0_39:
	s_cmpk_lt_i32 s54, 0x150
	s_cbranch_scc1 .Lconv_noremap
	s_sub_i32 s98, s87, 0xfc
	s_cmp_lt_u32 s98, 4
	s_cbranch_scc1 .Lconv_remap_up
	s_sub_i32 s98, s87, 0x14c
	s_cmp_lt_u32 s98, 4
	s_cbranch_scc0 .Lconv_noremap
	v_readlane_b32 s98, v253, 55
	s_mul_i32 s98, s98, 5
	s_ashr_i32 s98, s98, 4
	s_sub_i32 s87, s87, 0x50
	s_sub_i32 s86, s86, s98
	s_sub_i32 s28, s28, s98
	s_sub_i32 s26, s26, s98
	s_branch .Lconv_noremap
.Lconv_remap_up:
	v_readlane_b32 s98, v253, 55
	s_mul_i32 s98, s98, 5
	s_ashr_i32 s98, s98, 4
	s_add_i32 s87, s87, 0x50
	s_add_i32 s86, s86, s98
	s_add_i32 s28, s28, s98
	s_add_i32 s26, s26, s98
